# conversion tiles also in phase A tail (4096) and C1 tail (4096); hot loop heads pinned to 64-byte boundaries
# speedup vs baseline: 1.0104x; 1.0000x over previous
; template <bool ABF, bool BBF, class RowF, class ColF, class Epi>
; __device__ __forceinline__ void gemm_tile(char* smem, int K, RowF rowptr, ColF colptr, int ldb, Epi epi) {
;     ...
;   for (int k0 = 0; k0 < K; k0 += BK) {
;     if (k0 + BK < K) gload(k0 + BK);
;     const u16* As = As0 + cur * (GEMM_SMEM / 2);
;     const u16* Bs = As + BM * LDT;
;     {
;       bf16x8 af[2][4], bfr[2][4];
; #pragma unroll
;       for (int ks = 0; ks < 2; ks++) {
; #pragma unroll
;         for (int mi = 0; mi < 4; mi++) af[ks][mi] = *(const bf16x8*)&As[(wm * 64 + mi * 16 + l15) * LDT + (((ks * 4 + kg) ^ swz) << 3)];
; #pragma unroll
;         for (int ni = 0; ni < 4; ni++) bfr[ks][ni] = *(const bf16x8*)&Bs[(wn * 64 + ni * 16 + l15) * LDT + (((ks * 4 + kg) ^ swz) << 3)];
;       }
;       __builtin_amdgcn_sched_barrier(0);
; #pragma unroll
;       for (int ks = 0; ks < 2; ks++)
; #pragma unroll
;         for (int mi = 0; mi < 4; mi++)
; #pragma unroll
;           for (int ni = 0; ni < 4; ni++)
;             acc[mi][ni] = __builtin_amdgcn_mfma_f32_16x16x32_bf16(bfr[ks][ni], af[ks][mi], acc[mi][ni], 0, 0, 0);
;       __builtin_amdgcn_sched_barrier(0);
;     }
;     if (k0 + BK < K) sstore(cur ^ 1);
;     __syncthreads();
;     cur ^= 1;
;   }
.LBB0_111:
	s_add_i32 s4, s4, 64
	s_xor_b32 s5, s5, 1
	v_lshl_add_u64 v[106:107], v[106:107], 0, s[22:23]
	v_lshl_add_u64 v[108:109], v[108:109], 0, s[22:23]
	v_lshl_add_u64 v[110:111], v[110:111], 0, s[22:23]
	v_lshl_add_u64 v[112:113], v[112:113], 0, s[22:23]
	v_lshl_add_u64 v[114:115], v[114:115], 0, s[22:23]
	s_and_b64 vcc, exec, s[0:1]
	s_waitcnt lgkmcnt(0)
	s_barrier
	s_cbranch_vccnz .LBB0_116
	.p2align 6

; __device__ void phaseB(const Params& p, char* smem) {
;     ...
;     auto cload = [&](int u, float4 (&v)[4]) {
;       const int tile = u & 127, mat = (u >> 7) & 1, e = u >> 8;
;       const float* W = (mat ? p.w_up : p.w_gate) + (size_t)e * DM * DEXP + (size_t)((tile & 15) * 64) * DEXP + (tile >> 4) * 64;
; #pragma unroll
;       for (int i = 0; i < 4; i++) v[i] = *(const float4*)&W[(size_t)(tr + 16 * i) * DEXP + tc4];
;     };
;     auto cproc = [&](int u, float4 (&v)[4]) {
;       const int tile = u & 127, mat = (u >> 7) & 1, e = u >> 8;
;       u16* WT = (mat ? p.WuT : p.WgT) + (size_t)e * DEXP * DM;
;       const int k0 = (tile & 15) * 64, n0 = (tile >> 4) * 64;
;       __syncthreads();
; #pragma unroll
;       for (int i = 0; i < 4; i++) {
;         const int k = tr + 16 * i;
;         T[(tc4 + 0) * 72 + k] = f2bf(v[i].x); T[(tc4 + 1) * 72 + k] = f2bf(v[i].y);
;         T[(tc4 + 2) * 72 + k] = f2bf(v[i].z); T[(tc4 + 3) * 72 + k] = f2bf(v[i].w);
;       }
;       __syncthreads();
;       const int n = threadIdx.x >> 2, seg = (threadIdx.x & 3) * 16;
;       const u32x4 a = *(const u32x4*)&T[n * 72 + seg], b = *(const u32x4*)&T[n * 72 + seg + 8];
;       *(u32x4*)&WT[(size_t)(n0 + n) * DM + k0 + seg] = a;
;       *(u32x4*)&WT[(size_t)(n0 + n) * DM + k0 + seg + 8] = b;
;     };
.LBB0_383:
	s_mov_b64 exec, -1
	v_readlane_b32 s8, v240, 34
	v_readlane_b32 s9, v240, 35
	v_readlane_b32 s10, v240, 36
	v_readlane_b32 s11, v240, 37
	v_and_b32_e32 v0, 63, v128
	v_and_b32_e32 v1, 15, v0
	v_lshrrev_b32_e32 v2, 4, v0
	v_lshlrev_b32_e32 v3, 13, v1
	v_lshl_add_u32 v3, v2, 4, v3
	v_add_u32_e32 v4, 0x1000, v3
	v_lshlrev_b32_e32 v5, 13, v2
	v_lshl_add_u32 v5, v1, 3, v5
	v_add_u32_e32 v74, 0x0, v5
	v_add_u32_e32 v75, 0x1000, v5
	v_add_u32_e32 v76, 0x8000, v5
	v_add_u32_e32 v77, 0x9000, v5
	v_add_u32_e32 v78, 0x10000, v5
	v_add_u32_e32 v79, 0x11000, v5
	v_add_u32_e32 v80, 0x18000, v5
	v_add_u32_e32 v81, 0x19000, v5
	v_lshrrev_b32_e32 v9, 6, v128
	s_nop 0
	v_readfirstlane_b32 s12, v9
	s_nop 3
	v_readlane_b32 s16, v240, 42
	s_nop 3
	s_lshl_b32 s16, s16, 2
	s_add_u32 s16, s16, s12
	s_add_u32 s16, s16, 8192
	s_mov_b32 s13, s16
	s_branch .Lcvta_first

; __device__ void phaseB(const Params& p, char* smem) {
;     ...
;     auto cload = [&](int u, float4 (&v)[4]) {
;       const int tile = u & 127, mat = (u >> 7) & 1, e = u >> 8;
;       const float* W = (mat ? p.w_up : p.w_gate) + (size_t)e * DM * DEXP + (size_t)((tile & 15) * 64) * DEXP + (tile >> 4) * 64;
; #pragma unroll
;       for (int i = 0; i < 4; i++) v[i] = *(const float4*)&W[(size_t)(tr + 16 * i) * DEXP + tc4];
;     };
;     auto cproc = [&](int u, float4 (&v)[4]) {
;       const int tile = u & 127, mat = (u >> 7) & 1, e = u >> 8;
;       u16* WT = (mat ? p.WuT : p.WgT) + (size_t)e * DEXP * DM;
;       const int k0 = (tile & 15) * 64, n0 = (tile >> 4) * 64;
;       __syncthreads();
; #pragma unroll
;       for (int i = 0; i < 4; i++) {
;         const int k = tr + 16 * i;
;         T[(tc4 + 0) * 72 + k] = f2bf(v[i].x); T[(tc4 + 1) * 72 + k] = f2bf(v[i].y);
;         T[(tc4 + 2) * 72 + k] = f2bf(v[i].z); T[(tc4 + 3) * 72 + k] = f2bf(v[i].w);
;       }
;       __syncthreads();
;       const int n = threadIdx.x >> 2, seg = (threadIdx.x & 3) * 16;
;       const u32x4 a = *(const u32x4*)&T[n * 72 + seg], b = *(const u32x4*)&T[n * 72 + seg + 8];
;       *(u32x4*)&WT[(size_t)(n0 + n) * DM + k0 + seg] = a;
;       *(u32x4*)&WT[(size_t)(n0 + n) * DM + k0 + seg + 8] = b;
;     };
.Lcvta_first:
	s_cmp_ge_u32 s16, 12288
	s_cbranch_scc1 .Lcvta_done
	s_and_b32 s17, s16, 127
	s_lshr_b32 s18, s16, 8
	s_bitcmp1_b32 s16, 7
	s_cselect_b32 s20, s10, s8
	s_cselect_b32 s21, s11, s9
	s_cselect_b32 s22, s76, s74
	s_cselect_b32 s23, s77, s75
	s_and_b32 s19, s17, 15
	s_lshr_b32 s17, s17, 4
	s_lshl_b32 s26, s18, 21
	s_add_u32 s20, s20, s26
	s_addc_u32 s21, s21, 0
	s_lshl_b32 s26, s19, 17
	s_lshl_b32 s27, s17, 8
	s_add_u32 s26, s26, s27
	s_add_u32 s20, s20, s26
	s_addc_u32 s21, s21, 0
	s_lshl_b32 s26, s18, 20
	s_add_u32 s22, s22, s26
	s_addc_u32 s23, s23, 0
	s_lshl_b32 s26, s17, 17
	s_lshl_b32 s27, s19, 7
	s_add_u32 s26, s26, s27
	s_add_u32 s22, s22, s26
	s_addc_u32 s23, s23, 0
	global_load_dwordx4 v[10:13], v3, s[20:21] offset:0
	global_load_dwordx4 v[14:17], v3, s[20:21] offset:2048
	global_load_dwordx4 v[18:21], v4, s[20:21] offset:0
	global_load_dwordx4 v[22:25], v4, s[20:21] offset:2048
	global_load_dwordx4 v[26:29], v3, s[20:21] offset:64
	global_load_dwordx4 v[30:33], v3, s[20:21] offset:2112
	global_load_dwordx4 v[34:37], v4, s[20:21] offset:64
	global_load_dwordx4 v[38:41], v4, s[20:21] offset:2112
	global_load_dwordx4 v[42:45], v3, s[20:21] offset:128
	global_load_dwordx4 v[46:49], v3, s[20:21] offset:2176
	global_load_dwordx4 v[50:53], v4, s[20:21] offset:128
	global_load_dwordx4 v[54:57], v4, s[20:21] offset:2176
	global_load_dwordx4 v[58:61], v3, s[20:21] offset:192
	global_load_dwordx4 v[62:65], v3, s[20:21] offset:2240
	global_load_dwordx4 v[66:69], v4, s[20:21] offset:192
	global_load_dwordx4 v[70:73], v4, s[20:21] offset:2240
	s_waitcnt vmcnt(12)
	v_cvt_pk_bf16_f32 v82, v10, v14
	v_cvt_pk_bf16_f32 v83, v18, v22
	v_cvt_pk_bf16_f32 v84, v11, v15
	v_cvt_pk_bf16_f32 v85, v19, v23
	v_cvt_pk_bf16_f32 v86, v12, v16
	v_cvt_pk_bf16_f32 v87, v20, v24
	v_cvt_pk_bf16_f32 v88, v13, v17
	v_cvt_pk_bf16_f32 v89, v21, v25
	global_store_dwordx2 v74, v[82:83], s[22:23]
	global_store_dwordx2 v74, v[84:85], s[22:23] offset:2048
	global_store_dwordx2 v75, v[86:87], s[22:23]
	global_store_dwordx2 v75, v[88:89], s[22:23] offset:2048
	s_waitcnt vmcnt(12)
	v_cvt_pk_bf16_f32 v82, v26, v30
	v_cvt_pk_bf16_f32 v83, v34, v38
	v_cvt_pk_bf16_f32 v84, v27, v31
	v_cvt_pk_bf16_f32 v85, v35, v39
	v_cvt_pk_bf16_f32 v86, v28, v32
	v_cvt_pk_bf16_f32 v87, v36, v40
	v_cvt_pk_bf16_f32 v88, v29, v33
	v_cvt_pk_bf16_f32 v89, v37, v41
	global_store_dwordx2 v76, v[82:83], s[22:23]
	global_store_dwordx2 v76, v[84:85], s[22:23] offset:2048
	global_store_dwordx2 v77, v[86:87], s[22:23]
	global_store_dwordx2 v77, v[88:89], s[22:23] offset:2048
	s_waitcnt vmcnt(12)
	v_cvt_pk_bf16_f32 v82, v42, v46
	v_cvt_pk_bf16_f32 v83, v50, v54
	v_cvt_pk_bf16_f32 v84, v43, v47
	v_cvt_pk_bf16_f32 v85, v51, v55
	v_cvt_pk_bf16_f32 v86, v44, v48
	v_cvt_pk_bf16_f32 v87, v52, v56
	v_cvt_pk_bf16_f32 v88, v45, v49
	v_cvt_pk_bf16_f32 v89, v53, v57
	global_store_dwordx2 v78, v[82:83], s[22:23]
	global_store_dwordx2 v78, v[84:85], s[22:23] offset:2048
	global_store_dwordx2 v79, v[86:87], s[22:23]
	global_store_dwordx2 v79, v[88:89], s[22:23] offset:2048
	s_waitcnt vmcnt(12)
	v_cvt_pk_bf16_f32 v82, v58, v62
	v_cvt_pk_bf16_f32 v83, v66, v70
	v_cvt_pk_bf16_f32 v84, v59, v63
	v_cvt_pk_bf16_f32 v85, v67, v71
	v_cvt_pk_bf16_f32 v86, v60, v64
	v_cvt_pk_bf16_f32 v87, v68, v72
	v_cvt_pk_bf16_f32 v88, v61, v65
	v_cvt_pk_bf16_f32 v89, v69, v73
	global_store_dwordx2 v80, v[82:83], s[22:23]
	global_store_dwordx2 v80, v[84:85], s[22:23] offset:2048
	global_store_dwordx2 v81, v[86:87], s[22:23]
	global_store_dwordx2 v81, v[88:89], s[22:23] offset:2048
	s_branch .Lcvta_next
	s_nop 0
	s_nop 0
	s_nop 0
	s_nop 0

; template <int DK, bool HG, int MODE>
; __device__ void recur_unit(const Params& p, char* smem, int b, int h, char* img, int nstart, int nstep, int nend) {
;     ...
;   const int tid = threadIdx.x, lane = tid & 63, w = tid >> 6, l15 = lane & 15, kg = lane >> 4;
;   const int t = tid & 15, kgp = tid >> 4, k0 = kgp * KPT;
;   const int qcol = HG ? (h * 128) : (2048 + h * 64);
;   const int kcol = HG ? (512 + h * 128) : (2304 + h * 64);
;   const int vcol = HG ? (1024 + h * 128) : (2560 + h * 128);
;   const int gcol = HG ? (1536 + h * 128) : (3088 + h * 128);
;   const int ocol = HG ? (h * 128) : (512 + h * 128);
;   const float* gain = HG ? p.norm_h : p.norm_g;
;   float ba[KPT];
;   if (!HG && MODE == 1) {
;     __syncthreads();
;     for (int i = tid; i < 16 * 64; i += 256) Wa[i] = p.w_a2[(i >> 6) * 256 + h * 64 + (i & 63)];
; #pragma unroll
;     for (int i = 0; i < KPT; i++) ba[i] = p.b_a[h * 64 + k0 + i];
;     __syncthreads();
;   }
;   const float g0 = gain[h * 128 + w * 32 + l15], g1 = gain[h * 128 + w * 32 + 16 + l15];
;   f32x4 S[NKT][2];
; #pragma unroll
;   for (int i = 0; i < NKT; i++) { S[i][0] = f32x4{0, 0, 0, 0}; S[i][1] = f32x4{0, 0, 0, 0}; }
;   float4 pl[4];
;   uint4 pq, pk, pv;
;   u16 psg[8];
;   u32x4 imA[NIM], imB[NIM];
;   u16 psgB[8];
;   auto prefetch = [&](int n, u32x4 (&im)[NIM], u16 (&psg)[8]) {
;     if (MODE == 2) {
;       const char* src = img + (size_t)n * IMG;
; #pragma unroll
;       for (int i = 0; i < NIM; i++) if (tid * 16 + 4096 * i < IMG) im[i] = *(const u32x4*)(src + tid * 16 + 4096 * i);
;       {
;         const u32x4 g = *(const u32x4*)(p.P + ((size_t)b * SEQ + n * 16 + (tid >> 4)) * INC + gcol + (tid & 15) * 8);
;     ...
;   if (MODE == 2) {
;     prefetch(0, imA, psg);
;     prefetch(1, imB, psgB);
;     for (int n = 0; n < SEQ / 16; n += 2) {
;       if (n == 62) mid_barrier(p, smem);
;       step(n, imA, psg); step(n + 1, imB, psgB);
.Lrec_gla_entry:
	v_readlane_b32 s6, v240, 52
	v_readlane_b32 s2, v240, 24
	v_readlane_b32 s3, v240, 25
	s_nop 3
	s_sub_u32 s28, s6, 32
	s_mul_i32 s26, s28, 0x188000
	s_mul_hi_u32 s27, s28, 0x188000
	s_add_u32 s8, s80, s26
	s_addc_u32 s9, s81, s27
	s_lshr_b32 s26, s6, 2
	s_sub_u32 s26, s26, 8
	s_and_b32 s27, s6, 3
	s_mul_i32 s28, s26, 0xe10000
	s_add_u32 s10, s88, s28
	s_addc_u32 s11, s89, 0
	s_lshl_b32 s28, s27, 8
	s_add_u32 s28, s28, 0x1820
	s_add_u32 s10, s10, s28
	s_addc_u32 s11, s11, 0
	s_lshl_b32 s28, s26, 22
	s_add_u32 s12, s2, s28
	s_addc_u32 s13, s3, 0
	s_lshl_b32 s28, s27, 8
	s_add_u32 s28, s28, 0x400
	s_add_u32 s12, s12, s28
	s_addc_u32 s13, s13, 0
	s_sub_u32 s12, s12, 0x10000
	s_subb_u32 s13, s13, 0
	s_mov_b32 s30, 0x3c000000
	s_mov_b32 s4, 1
	s_mov_b32 s36, 0
	v_and_b32_e32 v137, 15, v128
	v_bfe_u32 v139, v128, 4, 2
	v_lshrrev_b32_e32 v142, 6, v128
	v_lshrrev_b32_e32 v178, 4, v128
	v_mul_u32_u24_e32 v202, 144, v137
	v_lshl_add_u32 v144, v139, 3, v202
	v_lshl_add_u32 v202, v142, 5, v137
	v_mul_u32_u24_e32 v202, 40, v202
	v_lshl_add_u32 v145, v139, 3, v202
	v_mul_u32_u24_e32 v202, 40, v137
	v_lshl_add_u32 v146, v139, 3, v202
	v_lshlrev_b32_e32 v147, 4, v139
	v_lshl_add_u32 v148, v142, 6, v147
	v_mul_u32_u24_e32 v202, 0x840, v139
	v_lshl_add_u32 v202, v142, 7, v202
	v_lshl_add_u32 v149, v137, 2, v202
	v_mul_u32_u24_e32 v202, 0x210, v178
	v_lshl_add_u32 v150, v137, 5, v202
	v_lshlrev_b32_e32 v151, 4, v128
	v_add_u32_e32 v152, 0x0, v151
	v_add_u32_e32 v153, 0x1000, v151
	v_add_u32_e32 v154, 0x2000, v151
	v_add_u32_e32 v172, 0x3000, v151
	s_movk_i32 s28, 16
	v_cmp_gt_u32_e64 s[24:25], s28, v128
	s_nop 1
	v_cndmask_b32_e64 v172, 0, v172, s[24:25]
	v_mul_u32_u24_e32 v202, 0x1c20, v178
	v_lshl_add_u32 v173, v137, 4, v202
	v_lshlrev_b32_e32 v202, 11, v178
	v_lshl_add_u32 v174, v137, 4, v202
	v_lshl_add_u32 v202, v142, 5, v137
	s_lshl_b32 s28, s27, 7
	v_add_lshl_u32 v202, s28, v202, 2
	global_load_dword v175, v202, s[64:65]
	global_load_dword v176, v202, s[64:65] offset:64
	v_lshlrev_b32_e32 v203, 2, v139
	v_cmp_gt_u32_e64 s[14:15], v203, v137
	v_add_u32_e32 v184, 1, v203
	v_cmp_gt_u32_e64 s[16:17], v184, v137
	v_add_u32_e32 v184, 2, v203
	v_cmp_gt_u32_e64 s[18:19], v184, v137
	v_add_u32_e32 v184, 3, v203
	v_cmp_gt_u32_e64 s[20:21], v184, v137
	v_cmp_eq_u32_e64 s[22:23], 0, v137
	v_mov_b32_e32 v177, 0x3727c5ac
	v_mov_b32_e32 v48, 0
	v_mov_b32_e32 v49, 0
	v_mov_b32_e32 v50, 0
	v_mov_b32_e32 v51, 0
	v_mov_b32_e32 v52, 0
	v_mov_b32_e32 v53, 0
	v_mov_b32_e32 v54, 0
	v_mov_b32_e32 v55, 0
	v_mov_b32_e32 v56, 0
	v_mov_b32_e32 v57, 0
	v_mov_b32_e32 v58, 0
	v_mov_b32_e32 v59, 0
	v_mov_b32_e32 v60, 0
	v_mov_b32_e32 v61, 0
	v_mov_b32_e32 v62, 0
	v_mov_b32_e32 v63, 0
	v_mov_b32_e32 v64, 0
	v_mov_b32_e32 v65, 0
	v_mov_b32_e32 v66, 0
	v_mov_b32_e32 v67, 0
	v_mov_b32_e32 v68, 0
	v_mov_b32_e32 v69, 0
	v_mov_b32_e32 v70, 0
	v_mov_b32_e32 v71, 0
	v_mov_b32_e32 v72, 0
	v_mov_b32_e32 v73, 0
	v_mov_b32_e32 v74, 0
	v_mov_b32_e32 v75, 0
	v_mov_b32_e32 v76, 0
	v_mov_b32_e32 v77, 0
	v_mov_b32_e32 v78, 0
	v_mov_b32_e32 v79, 0
	global_load_dwordx4 v[0:3], v152, s[8:9]
	global_load_dwordx4 v[4:7], v153, s[8:9]
	global_load_dwordx4 v[8:11], v154, s[8:9]
	global_load_dwordx4 v[12:15], v172, s[8:9]
	s_add_u32 s8, s8, 0x3100
	s_addc_u32 s9, s9, 0
	global_load_dwordx4 v[20:23], v152, s[8:9]
	global_load_dwordx4 v[24:27], v153, s[8:9]
	global_load_dwordx4 v[28:31], v154, s[8:9]
	global_load_dwordx4 v[32:35], v172, s[8:9]
	s_add_u32 s8, s8, 0x3100
	s_addc_u32 s9, s9, 0
	s_waitcnt vmcnt(4)
	ds_write_b128 v151, v[0:3] offset:0
	ds_write_b128 v151, v[4:7] offset:4096
	ds_write_b128 v151, v[8:11] offset:8192
	s_mov_b64 s[26:27], exec
	s_and_b64 exec, exec, s[24:25]
	ds_write_b128 v151, v[12:15] offset:12288
	s_mov_b64 exec, s[26:27]
	global_load_dwordx4 v[0:3], v152, s[8:9]
	global_load_dwordx4 v[4:7], v153, s[8:9]
	global_load_dwordx4 v[8:11], v154, s[8:9]
	global_load_dwordx4 v[12:15], v172, s[8:9]
	s_add_u32 s8, s8, 0x3100
	s_addc_u32 s9, s9, 0
	s_waitcnt lgkmcnt(0)
	.p2align 6

; template <int DK, bool HG, int MODE>
; __device__ void recur_unit(const Params& p, char* smem, int b, int h, char* img, int nstart, int nstep, int nend) {
;     ...
;   const int tid = threadIdx.x, lane = tid & 63, w = tid >> 6, l15 = lane & 15, kg = lane >> 4;
;   const int t = tid & 15, kgp = tid >> 4, k0 = kgp * KPT;
;   const int qcol = HG ? (h * 128) : (2048 + h * 64);
;   const int kcol = HG ? (512 + h * 128) : (2304 + h * 64);
;   const int vcol = HG ? (1024 + h * 128) : (2560 + h * 128);
;   const int gcol = HG ? (1536 + h * 128) : (3088 + h * 128);
;   const int ocol = HG ? (h * 128) : (512 + h * 128);
;   const float* gain = HG ? p.norm_h : p.norm_g;
;   float ba[KPT];
;   if (!HG && MODE == 1) {
;     __syncthreads();
;     for (int i = tid; i < 16 * 64; i += 256) Wa[i] = p.w_a2[(i >> 6) * 256 + h * 64 + (i & 63)];
; #pragma unroll
;     for (int i = 0; i < KPT; i++) ba[i] = p.b_a[h * 64 + k0 + i];
;     __syncthreads();
;   }
;   const float g0 = gain[h * 128 + w * 32 + l15], g1 = gain[h * 128 + w * 32 + 16 + l15];
;   f32x4 S[NKT][2];
; #pragma unroll
;   for (int i = 0; i < NKT; i++) { S[i][0] = f32x4{0, 0, 0, 0}; S[i][1] = f32x4{0, 0, 0, 0}; }
;   float4 pl[4];
;   uint4 pq, pk, pv;
;   u16 psg[8];
;   u32x4 imA[NIM], imB[NIM];
;   u16 psgB[8];
;   auto prefetch = [&](int n, u32x4 (&im)[NIM], u16 (&psg)[8]) {
;     if (MODE == 2) {
;       const char* src = img + (size_t)n * IMG;
; #pragma unroll
;       for (int i = 0; i < NIM; i++) if (tid * 16 + 4096 * i < IMG) im[i] = *(const u32x4*)(src + tid * 16 + 4096 * i);
;       {
;         const u32x4 g = *(const u32x4*)(p.P + ((size_t)b * SEQ + n * 16 + (tid >> 4)) * INC + gcol + (tid & 15) * 8);
;     ...
;   if (MODE == 2) {
;     prefetch(0, imA, psg);
;     prefetch(1, imB, psgB);
;     for (int n = 0; n < SEQ / 16; n += 2) {
;       if (n == 62) mid_barrier(p, smem);
;       step(n, imA, psg); step(n + 1, imB, psgB);
.Lrec_hg_entry:
	v_readlane_b32 s6, v240, 52
	v_readlane_b32 s2, v240, 24
	v_readlane_b32 s3, v240, 25
	s_nop 3
	s_mul_i32 s26, s6, 0x260000
	s_mul_hi_u32 s27, s6, 0x260000
	s_add_u32 s8, s78, s26
	s_addc_u32 s9, s79, s27
	s_lshr_b32 s26, s6, 2
	s_and_b32 s27, s6, 3
	s_mul_i32 s28, s26, 0xe10000
	s_add_u32 s10, s88, s28
	s_addc_u32 s11, s89, 0
	s_lshl_b32 s28, s27, 8
	s_add_u32 s28, s28, 0xc00
	s_add_u32 s10, s10, s28
	s_addc_u32 s11, s11, 0
	s_lshl_b32 s28, s26, 22
	s_add_u32 s12, s2, s28
	s_addc_u32 s13, s3, 0
	s_lshl_b32 s28, s27, 8
	s_add_u32 s12, s12, s28
	s_addc_u32 s13, s13, 0
	s_sub_u32 s12, s12, 0x10000
	s_subb_u32 s13, s13, 0
	s_mov_b32 s30, 0x3c000000
	s_mov_b32 s4, 0
	s_mov_b32 s36, 0
	v_and_b32_e32 v137, 15, v128
	v_bfe_u32 v139, v128, 4, 2
	v_lshrrev_b32_e32 v142, 6, v128
	v_lshrrev_b32_e32 v178, 4, v128
	v_mul_u32_u24_e32 v202, 272, v137
	v_lshl_add_u32 v144, v139, 3, v202
	v_lshl_add_u32 v202, v142, 5, v137
	v_mul_u32_u24_e32 v202, 40, v202
	v_lshl_add_u32 v145, v139, 3, v202
	v_mul_u32_u24_e32 v202, 40, v137
	v_lshl_add_u32 v146, v139, 3, v202
	v_lshlrev_b32_e32 v147, 4, v139
	v_lshl_add_u32 v148, v142, 6, v147
	v_mul_u32_u24_e32 v202, 0x840, v139
	v_lshl_add_u32 v202, v142, 7, v202
	v_lshl_add_u32 v149, v137, 2, v202
	v_mul_u32_u24_e32 v202, 0x210, v178
	v_lshl_add_u32 v150, v137, 5, v202
	v_lshlrev_b32_e32 v151, 4, v128
	v_add_u32_e32 v152, 0x0, v151
	v_add_u32_e32 v153, 0x1000, v151
	v_add_u32_e32 v154, 0x2000, v151
	v_add_u32_e32 v155, 0x3000, v151
	v_add_u32_e32 v172, 0x4000, v151
	s_movk_i32 s28, 192
	v_cmp_gt_u32_e64 s[24:25], s28, v128
	s_nop 1
	v_cndmask_b32_e64 v172, 0, v172, s[24:25]
	v_mul_u32_u24_e32 v202, 0x1c20, v178
	v_lshl_add_u32 v173, v137, 4, v202
	v_lshlrev_b32_e32 v202, 11, v178
	v_lshl_add_u32 v174, v137, 4, v202
	v_lshl_add_u32 v202, v142, 5, v137
	s_lshl_b32 s28, s27, 7
	v_add_lshl_u32 v202, s28, v202, 2
	global_load_dword v175, v202, s[62:63]
	global_load_dword v176, v202, s[62:63] offset:64
	v_lshlrev_b32_e32 v203, 2, v139
	v_cmp_gt_u32_e64 s[14:15], v203, v137
	v_add_u32_e32 v184, 1, v203
	v_cmp_gt_u32_e64 s[16:17], v184, v137
	v_add_u32_e32 v184, 2, v203
	v_cmp_gt_u32_e64 s[18:19], v184, v137
	v_add_u32_e32 v184, 3, v203
	v_cmp_gt_u32_e64 s[20:21], v184, v137
	v_cmp_eq_u32_e64 s[22:23], 0, v137
	v_mov_b32_e32 v177, 0x3727c5ac
	v_mov_b32_e32 v48, 0
	v_mov_b32_e32 v49, 0
	v_mov_b32_e32 v50, 0
	v_mov_b32_e32 v51, 0
	v_mov_b32_e32 v52, 0
	v_mov_b32_e32 v53, 0
	v_mov_b32_e32 v54, 0
	v_mov_b32_e32 v55, 0
	v_mov_b32_e32 v56, 0
	v_mov_b32_e32 v57, 0
	v_mov_b32_e32 v58, 0
	v_mov_b32_e32 v59, 0
	v_mov_b32_e32 v60, 0
	v_mov_b32_e32 v61, 0
	v_mov_b32_e32 v62, 0
	v_mov_b32_e32 v63, 0
	v_mov_b32_e32 v64, 0
	v_mov_b32_e32 v65, 0
	v_mov_b32_e32 v66, 0
	v_mov_b32_e32 v67, 0
	v_mov_b32_e32 v68, 0
	v_mov_b32_e32 v69, 0
	v_mov_b32_e32 v70, 0
	v_mov_b32_e32 v71, 0
	v_mov_b32_e32 v72, 0
	v_mov_b32_e32 v73, 0
	v_mov_b32_e32 v74, 0
	v_mov_b32_e32 v75, 0
	v_mov_b32_e32 v76, 0
	v_mov_b32_e32 v77, 0
	v_mov_b32_e32 v78, 0
	v_mov_b32_e32 v79, 0
	v_mov_b32_e32 v80, 0
	v_mov_b32_e32 v81, 0
	v_mov_b32_e32 v82, 0
	v_mov_b32_e32 v83, 0
	v_mov_b32_e32 v84, 0
	v_mov_b32_e32 v85, 0
	v_mov_b32_e32 v86, 0
	v_mov_b32_e32 v87, 0
	v_mov_b32_e32 v88, 0
	v_mov_b32_e32 v89, 0
	v_mov_b32_e32 v90, 0
	v_mov_b32_e32 v91, 0
	v_mov_b32_e32 v92, 0
	v_mov_b32_e32 v93, 0
	v_mov_b32_e32 v94, 0
	v_mov_b32_e32 v95, 0
	v_mov_b32_e32 v96, 0
	v_mov_b32_e32 v97, 0
	v_mov_b32_e32 v98, 0
	v_mov_b32_e32 v99, 0
	v_mov_b32_e32 v100, 0
	v_mov_b32_e32 v101, 0
	v_mov_b32_e32 v102, 0
	v_mov_b32_e32 v103, 0
	v_mov_b32_e32 v104, 0
	v_mov_b32_e32 v105, 0
	v_mov_b32_e32 v106, 0
	v_mov_b32_e32 v107, 0
	v_mov_b32_e32 v108, 0
	v_mov_b32_e32 v109, 0
	v_mov_b32_e32 v110, 0
	v_mov_b32_e32 v111, 0
	global_load_dwordx4 v[0:3], v152, s[8:9]
	global_load_dwordx4 v[4:7], v153, s[8:9]
	global_load_dwordx4 v[8:11], v154, s[8:9]
	global_load_dwordx4 v[12:15], v155, s[8:9]
	global_load_dwordx4 v[16:19], v172, s[8:9]
	s_add_u32 s8, s8, 0x4c00
	s_addc_u32 s9, s9, 0
	global_load_dwordx4 v[20:23], v152, s[8:9]
	global_load_dwordx4 v[24:27], v153, s[8:9]
	global_load_dwordx4 v[28:31], v154, s[8:9]
	global_load_dwordx4 v[32:35], v155, s[8:9]
	global_load_dwordx4 v[36:39], v172, s[8:9]
	s_add_u32 s8, s8, 0x4c00
	s_addc_u32 s9, s9, 0
	s_waitcnt vmcnt(5)
	ds_write_b128 v151, v[0:3] offset:0
	ds_write_b128 v151, v[4:7] offset:4096
	ds_write_b128 v151, v[8:11] offset:8192
	ds_write_b128 v151, v[12:15] offset:12288
	s_mov_b64 s[26:27], exec
	s_and_b64 exec, exec, s[24:25]
	ds_write_b128 v151, v[16:19] offset:16384
	s_mov_b64 exec, s[26:27]
	global_load_dwordx4 v[0:3], v152, s[8:9]
	global_load_dwordx4 v[4:7], v153, s[8:9]
	global_load_dwordx4 v[8:11], v154, s[8:9]
	global_load_dwordx4 v[12:15], v155, s[8:9]
	global_load_dwordx4 v[16:19], v172, s[8:9]
	s_add_u32 s8, s8, 0x4c00
	s_addc_u32 s9, s9, 0
	s_waitcnt lgkmcnt(0)
	.p2align 6

; __device__ void phaseB(const Params& p, char* smem) {
;     ...
;     auto cload = [&](int u, float4 (&v)[4]) {
;       const int tile = u & 127, mat = (u >> 7) & 1, e = u >> 8;
;       const float* W = (mat ? p.w_up : p.w_gate) + (size_t)e * DM * DEXP + (size_t)((tile & 15) * 64) * DEXP + (tile >> 4) * 64;
; #pragma unroll
;       for (int i = 0; i < 4; i++) v[i] = *(const float4*)&W[(size_t)(tr + 16 * i) * DEXP + tc4];
;     };
;     auto cproc = [&](int u, float4 (&v)[4]) {
;       const int tile = u & 127, mat = (u >> 7) & 1, e = u >> 8;
;       u16* WT = (mat ? p.WuT : p.WgT) + (size_t)e * DEXP * DM;
;       const int k0 = (tile & 15) * 64, n0 = (tile >> 4) * 64;
;       __syncthreads();
; #pragma unroll
;       for (int i = 0; i < 4; i++) {
;         const int k = tr + 16 * i;
;         T[(tc4 + 0) * 72 + k] = f2bf(v[i].x); T[(tc4 + 1) * 72 + k] = f2bf(v[i].y);
;         T[(tc4 + 2) * 72 + k] = f2bf(v[i].z); T[(tc4 + 3) * 72 + k] = f2bf(v[i].w);
;       }
;       __syncthreads();
;       const int n = threadIdx.x >> 2, seg = (threadIdx.x & 3) * 16;
;       const u32x4 a = *(const u32x4*)&T[n * 72 + seg], b = *(const u32x4*)&T[n * 72 + seg + 8];
;       *(u32x4*)&WT[(size_t)(n0 + n) * DM + k0 + seg] = a;
;       *(u32x4*)&WT[(size_t)(n0 + n) * DM + k0 + seg + 8] = b;
;     };
;     auto conv_range = [&](int u, int uend) -> int {
;       float4 va[4], vb[4];
;       if (u < uend) cload(u, va);
;       while (u < uend) {
;         if (u + nb < uend) cload(u + nb, vb);
;         cproc(u, va);
;         u += nb;
;         if (u >= uend) break;
;         if (u + nb < uend) cload(u + nb, va);
;         cproc(u, vb);
;         u += nb;
;       }
;       return u;
;     };
.LBB0_825:
	v_and_b32_e32 v96, 60, v127
	s_cmpk_gt_i32 s4, 0x13ff
	v_lshlrev_b32_e32 v98, 11, v132
	v_lshlrev_b32_e32 v100, 2, v96
	v_and_b32_e32 v97, 48, v140
	v_lshlrev_b32_e32 v137, 1, v132
	s_cbranch_scc1 .LBB0_836
	s_ashr_i32 s0, s4, 8
	v_readlane_b32 s8, v240, 26
	s_bitcmp0_b32 s4, 7
	v_readlane_b32 s16, v240, 34
	v_readlane_b32 s17, v240, 35
	v_readlane_b32 s18, v240, 36
	v_readlane_b32 s19, v240, 37
	s_cselect_b32 s2, s17, s19
	s_cselect_b32 s3, s16, s18
	s_ashr_i32 s1, s0, 31
	s_lshl_b64 s[0:1], s[0:1], 21
	s_add_u32 s0, s3, s0
	v_readlane_b32 s9, v240, 27
	s_addc_u32 s1, s2, s1
	s_lshl_b32 s2, s40, 17
	s_lshl_b32 s9, s40, 15
	s_and_b32 s2, s2, 0x1e0000
	s_add_u32 s0, s0, s2
	s_addc_u32 s1, s1, 0
	s_lshl_b32 s2, s4, 4
	s_and_b32 s2, s2, 0x700
	s_add_u32 s0, s0, s2
	s_waitcnt vmcnt(2)
	v_mov_b32_e32 v33, 0
	s_addc_u32 s1, s1, 0
	v_mov_b32_e32 v99, v33
	v_add_u32_e32 v34, 0x8000, v98
	v_mov_b32_e32 v35, v33
	s_waitcnt vmcnt(1)
	v_add_u32_e32 v36, 0x10000, v98
	v_mov_b32_e32 v37, v33
	v_add_u32_e32 v38, 0x18000, v98
	v_mov_b32_e32 v39, v33
	s_waitcnt vmcnt(0)
	v_lshl_add_u64 v[0:1], s[0:1], 0, v[98:99]
	v_mov_b32_e32 v101, v33
	v_lshl_add_u64 v[2:3], s[0:1], 0, v[34:35]
	v_lshl_add_u64 v[8:9], s[0:1], 0, v[36:37]
	v_lshl_add_u64 v[10:11], s[0:1], 0, v[38:39]
	v_lshl_add_u64 v[0:1], v[0:1], 0, v[100:101]
	v_lshl_add_u64 v[4:5], v[2:3], 0, v[100:101]
	v_lshl_add_u64 v[8:9], v[8:9], 0, v[100:101]
	v_lshl_add_u64 v[12:13], v[10:11], 0, v[100:101]
	global_load_dwordx4 v[0:3], v[0:1], off
	s_nop 0
	global_load_dwordx4 v[4:7], v[4:5], off
	s_nop 0
	global_load_dwordx4 v[8:11], v[8:9], off
	s_nop 0
	global_load_dwordx4 v[12:15], v[12:13], off
	v_readlane_b32 s14, v240, 32
	s_lshl_b32 s0, s5, 15
	v_readlane_b32 s10, v240, 28
	v_mul_u32_u24_e32 v16, 0x90, v96
	s_add_i32 s14, s0, s9
	s_add_i32 s0, s5, s24
	v_readlane_b32 s11, v240, 29
	v_readlane_b32 s12, v240, 30
	v_readlane_b32 s13, v240, 31
	v_add3_u32 v40, 0, v16, v137
	v_mul_u32_u24_e32 v16, 0x90, v135
	v_lshlrev_b32_e32 v17, 1, v97
	s_lshl_b32 s3, s40, 2
	s_lshl_b32 s6, s24, 3
	s_lshl_b32 s10, s24, 2
	s_add_i32 s0, s0, s40
	v_add3_u32 v41, 0, v16, v17
	s_lshl_b32 s11, s4, 6
	s_lshl_b32 s2, s24, 7
	s_lshl_b32 s12, s5, 2
	s_lshl_b32 s7, s24, 1
	s_lshl_b32 s8, s24, 16
	s_add_i32 s9, s6, s3
	s_add_i32 s10, s10, s3
	s_lshl_b32 s13, s0, 6
	s_lshl_b32 s5, s24, 15
	v_readlane_b32 s15, v240, 33
	v_readlane_b32 s20, v240, 38
	v_readlane_b32 s21, v240, 39
	v_readlane_b32 s22, v240, 40
	v_readlane_b32 s23, v240, 41
	s_branch .LBB0_828
.LBB0_827:
	v_cvt_pk_bf16_f32 v32, v20, s0
	s_barrier
	ds_write_b16 v40, v32
	v_cvt_pk_bf16_f32 v32, v21, s0
	ds_write_b16 v40, v32 offset:144
	v_cvt_pk_bf16_f32 v32, v22, s0
	ds_write_b16 v40, v32 offset:288
	v_cvt_pk_bf16_f32 v32, v23, s0
	ds_write_b16 v40, v32 offset:432
	v_cvt_pk_bf16_f32 v32, v16, s0
	ds_write_b16 v40, v32 offset:32
	v_cvt_pk_bf16_f32 v32, v17, s0
	ds_write_b16 v40, v32 offset:176
	v_cvt_pk_bf16_f32 v32, v18, s0
	ds_write_b16 v40, v32 offset:320
	v_cvt_pk_bf16_f32 v32, v19, s0
	ds_write_b16 v40, v32 offset:464
	v_cvt_pk_bf16_f32 v32, v28, s0
	ds_write_b16 v40, v32 offset:64
	v_cvt_pk_bf16_f32 v32, v29, s0
	ds_write_b16 v40, v32 offset:208
	v_cvt_pk_bf16_f32 v32, v30, s0
	ds_write_b16 v40, v32 offset:352
	v_cvt_pk_bf16_f32 v32, v31, s0
	ds_write_b16 v40, v32 offset:496
	v_cvt_pk_bf16_f32 v32, v24, s0
	s_add_i32 s4, s25, s24
	ds_write_b16 v40, v32 offset:96
	v_cvt_pk_bf16_f32 v32, v25, s0
	s_bitcmp0_b32 s25, 7
	ds_write_b16 v40, v32 offset:240
	v_cvt_pk_bf16_f32 v32, v26, s0
	s_cselect_b32 s14, s75, s77
	s_cselect_b32 s16, s74, s76
	ds_write_b16 v40, v32 offset:384
	v_cvt_pk_bf16_f32 v32, v27, s0
	s_add_i32 s0, s10, s12
	s_and_b32 s17, s0, 0x1c0
	s_ashr_i32 s0, s25, 8
	ds_write_b16 v40, v32 offset:528
	s_ashr_i32 s1, s0, 31
	s_waitcnt lgkmcnt(0)
	s_barrier
	ds_read_b128 v[42:45], v41
	ds_read_b128 v[46:49], v41 offset:16
	s_and_b32 s18, s13, 0x3c0
	s_lshl_b64 s[0:1], s[0:1], 20
	s_add_u32 s0, s16, s0
	v_add_lshl_u32 v32, s17, v135, 10
	s_addc_u32 s1, s14, s1
	v_or3_b32 v32, v32, s18, v97
	s_add_i32 s11, s11, s2
	s_add_i32 s12, s12, s6
	s_add_i32 s13, s13, s2
	v_lshlrev_b32_e32 v32, 1, v32
	s_cmpk_gt_i32 s4, 0x13ff
	s_waitcnt lgkmcnt(1)
	global_store_dwordx4 v32, v[42:45], s[0:1]
	s_waitcnt lgkmcnt(0)
	global_store_dwordx4 v32, v[46:49], s[0:1] offset:16
	s_cselect_b64 s[0:1], -1, 0
	s_mov_b32 s25, s4
	s_mov_b32 s14, s15
	s_and_b64 vcc, exec, s[0:1]
	s_cbranch_vccnz .LBB0_837
; __device__ void phaseB(const Params& p, char* smem) {
;     ...
;     auto cload = [&](int u, float4 (&v)[4]) {
;       const int tile = u & 127, mat = (u >> 7) & 1, e = u >> 8;
;       const float* W = (mat ? p.w_up : p.w_gate) + (size_t)e * DM * DEXP + (size_t)((tile & 15) * 64) * DEXP + (tile >> 4) * 64;
; #pragma unroll
;       for (int i = 0; i < 4; i++) v[i] = *(const float4*)&W[(size_t)(tr + 16 * i) * DEXP + tc4];
;     };
;     auto cproc = [&](int u, float4 (&v)[4]) {
;       const int tile = u & 127, mat = (u >> 7) & 1, e = u >> 8;
;       u16* WT = (mat ? p.WuT : p.WgT) + (size_t)e * DEXP * DM;
;       const int k0 = (tile & 15) * 64, n0 = (tile >> 4) * 64;
;       __syncthreads();
; #pragma unroll
;       for (int i = 0; i < 4; i++) {
;         const int k = tr + 16 * i;
;         T[(tc4 + 0) * 72 + k] = f2bf(v[i].x); T[(tc4 + 1) * 72 + k] = f2bf(v[i].y);
;         T[(tc4 + 2) * 72 + k] = f2bf(v[i].z); T[(tc4 + 3) * 72 + k] = f2bf(v[i].w);
;       }
;       __syncthreads();
;       const int n = threadIdx.x >> 2, seg = (threadIdx.x & 3) * 16;
;       const u32x4 a = *(const u32x4*)&T[n * 72 + seg], b = *(const u32x4*)&T[n * 72 + seg + 8];
;       *(u32x4*)&WT[(size_t)(n0 + n) * DM + k0 + seg] = a;
;       *(u32x4*)&WT[(size_t)(n0 + n) * DM + k0 + seg + 8] = b;
;     };
;     auto conv_range = [&](int u, int uend) -> int {
;       float4 va[4], vb[4];
;       if (u < uend) cload(u, va);
;       while (u < uend) {
;         if (u + nb < uend) cload(u + nb, vb);
;         cproc(u, va);
;         u += nb;
;         if (u >= uend) break;
;         if (u + nb < uend) cload(u + nb, va);
;         cproc(u, vb);
;         u += nb;
;       }
;       return u;
;     };
.LBB0_828:
	s_add_i32 s25, s4, s24
	s_cmpk_lt_i32 s25, 0x1400
	s_cselect_b64 s[0:1], -1, 0
	s_cmpk_gt_i32 s25, 0x13ff
	s_cbranch_scc1 .LBB0_830
	s_ashr_i32 s16, s25, 8
	v_readlane_b32 s36, v240, 26
	s_bitcmp0_b32 s25, 7
	v_readlane_b32 s44, v240, 34
	v_readlane_b32 s45, v240, 35
	v_readlane_b32 s46, v240, 36
	v_readlane_b32 s47, v240, 37
	s_cselect_b32 s15, s45, s47
	s_cselect_b32 s18, s44, s46
	s_ashr_i32 s17, s16, 31
	s_lshl_b64 s[16:17], s[16:17], 21
	s_add_u32 s16, s18, s16
	s_addc_u32 s15, s15, s17
	s_add_i32 s17, s5, s14
	s_and_b32 s17, s17, 0x78000
	s_lshl_b32 s17, s17, 2
	s_add_u32 s16, s16, s17
	s_addc_u32 s15, s15, 0
	s_add_i32 s17, s10, s12
	s_and_b32 s17, s17, 0x1c0
	s_lshl_b32 s17, s17, 2
	s_add_u32 s16, s16, s17
	s_addc_u32 s17, s15, 0
	v_lshl_add_u64 v[16:17], s[16:17], 0, v[98:99]
	v_lshlrev_b32_e32 v32, 2, v96
	v_lshl_add_u64 v[18:19], s[16:17], 0, v[34:35]
	v_lshl_add_u64 v[24:25], s[16:17], 0, v[36:37]
	v_lshl_add_u64 v[26:27], s[16:17], 0, v[38:39]
	v_lshl_add_u64 v[16:17], v[16:17], 0, v[32:33]
	v_lshl_add_u64 v[18:19], v[18:19], 0, v[32:33]
	v_lshl_add_u64 v[24:25], v[24:25], 0, v[32:33]
	v_lshl_add_u64 v[26:27], v[26:27], 0, v[32:33]
	global_load_dwordx4 v[20:23], v[16:17], off
	s_nop 0
	global_load_dwordx4 v[16:19], v[18:19], off
	s_nop 0
	global_load_dwordx4 v[28:31], v[24:25], off
	s_nop 0
	global_load_dwordx4 v[24:27], v[26:27], off
	v_readlane_b32 s37, v240, 27
	v_readlane_b32 s38, v240, 28
	v_readlane_b32 s39, v240, 29
	v_readlane_b32 s40, v240, 30
	v_readlane_b32 s41, v240, 31
	v_readlane_b32 s42, v240, 32
	v_readlane_b32 s43, v240, 33
	v_readlane_b32 s48, v240, 38
	v_readlane_b32 s49, v240, 39
	v_readlane_b32 s50, v240, 40
	v_readlane_b32 s51, v240, 41
.LBB0_830:
	s_waitcnt vmcnt(3)
	v_cvt_pk_bf16_f32 v32, v0, s0
	s_barrier
	ds_write_b16 v40, v32
	v_cvt_pk_bf16_f32 v32, v1, s0
	ds_write_b16 v40, v32 offset:144
	v_cvt_pk_bf16_f32 v32, v2, s0
	ds_write_b16 v40, v32 offset:288
	v_cvt_pk_bf16_f32 v32, v3, s0
	ds_write_b16 v40, v32 offset:432
	s_waitcnt vmcnt(2)
	v_cvt_pk_bf16_f32 v32, v4, s0
	ds_write_b16 v40, v32 offset:32
	v_cvt_pk_bf16_f32 v32, v5, s0
	ds_write_b16 v40, v32 offset:176
	v_cvt_pk_bf16_f32 v32, v6, s0
	ds_write_b16 v40, v32 offset:320
	v_cvt_pk_bf16_f32 v32, v7, s0
	ds_write_b16 v40, v32 offset:464
	s_waitcnt vmcnt(1)
	v_cvt_pk_bf16_f32 v32, v8, s0
	ds_write_b16 v40, v32 offset:64
	v_cvt_pk_bf16_f32 v32, v9, s0
	ds_write_b16 v40, v32 offset:208
	v_cvt_pk_bf16_f32 v32, v10, s0
	ds_write_b16 v40, v32 offset:352
	v_cvt_pk_bf16_f32 v32, v11, s0
	ds_write_b16 v40, v32 offset:496
	s_waitcnt vmcnt(0)
	v_cvt_pk_bf16_f32 v32, v12, s0
	ds_write_b16 v40, v32 offset:96
	v_cvt_pk_bf16_f32 v32, v13, s0
	s_bitcmp0_b32 s4, 7
	ds_write_b16 v40, v32 offset:240
	v_cvt_pk_bf16_f32 v32, v14, s0
	s_cselect_b32 s15, s75, s77
	s_cselect_b32 s18, s74, s76
	ds_write_b16 v40, v32 offset:384
	v_cvt_pk_bf16_f32 v32, v15, s0
	s_add_i32 s16, s3, s12
	ds_write_b16 v40, v32 offset:528
	s_and_b32 s19, s16, 0x1c0
	s_ashr_i32 s16, s4, 8
	s_waitcnt lgkmcnt(0)
	s_barrier
	ds_read_b128 v[42:45], v41
	ds_read_b128 v[46:49], v41 offset:16
	s_ashr_i32 s17, s16, 31
	s_and_b32 s20, s11, 0x3c0
	s_lshl_b64 s[16:17], s[16:17], 20
	v_add_lshl_u32 v32, s19, v135, 10
	s_add_u32 s16, s18, s16
	v_or3_b32 v32, v32, s20, v97
	s_addc_u32 s17, s15, s17
	v_lshlrev_b32_e32 v32, 1, v32
	s_andn2_b64 vcc, exec, s[0:1]
	s_mov_b64 s[0:1], -1
	s_waitcnt lgkmcnt(1)
	global_store_dwordx4 v32, v[42:45], s[16:17]
	s_waitcnt lgkmcnt(0)
	global_store_dwordx4 v32, v[46:49], s[16:17] offset:16
	s_cbranch_vccnz .LBB0_835
	s_add_i32 s4, s7, s4
	s_cmpk_lt_i32 s4, 0x1400
	s_cbranch_scc1 .LBB0_833
	s_add_i32 s15, s14, s8
	s_mov_b64 s[0:1], 0

; template <bool ABF, bool BBF, class RowF, class ColF, class Epi>
; __device__ __forceinline__ void gemm_tile(char* smem, int K, RowF rowptr, ColF colptr, int ldb, Epi epi) {
;     ...
;   for (int k0 = 0; k0 < K; k0 += BK) {
;     if (k0 + BK < K) gload(k0 + BK);
;     const u16* As = As0 + cur * (GEMM_SMEM / 2);
;     const u16* Bs = As + BM * LDT;
;     {
;       bf16x8 af[2][4], bfr[2][4];
; #pragma unroll
;       for (int ks = 0; ks < 2; ks++) {
; #pragma unroll
;         for (int mi = 0; mi < 4; mi++) af[ks][mi] = *(const bf16x8*)&As[(wm * 64 + mi * 16 + l15) * LDT + (((ks * 4 + kg) ^ swz) << 3)];
; #pragma unroll
;         for (int ni = 0; ni < 4; ni++) bfr[ks][ni] = *(const bf16x8*)&Bs[(wn * 64 + ni * 16 + l15) * LDT + (((ks * 4 + kg) ^ swz) << 3)];
;       }
;       __builtin_amdgcn_sched_barrier(0);
; #pragma unroll
;       for (int ks = 0; ks < 2; ks++)
; #pragma unroll
;         for (int mi = 0; mi < 4; mi++)
; #pragma unroll
;           for (int ni = 0; ni < 4; ni++)
;             acc[mi][ni] = __builtin_amdgcn_mfma_f32_16x16x32_bf16(bfr[ks][ni], af[ks][mi], acc[mi][ni], 0, 0, 0);
;       __builtin_amdgcn_sched_barrier(0);
;     }
;     if (k0 + BK < K) sstore(cur ^ 1);
;     __syncthreads();
;     cur ^= 1;
;   }
.LBB0_900:
	s_add_i32 s6, s6, 64
	s_xor_b32 s37, s37, 1
	v_lshl_add_u64 v[142:143], v[142:143], 0, s[2:3]
	v_lshl_add_u64 v[144:145], v[144:145], 0, s[2:3]
	v_lshl_add_u64 v[146:147], v[146:147], 0, s[2:3]
	v_lshl_add_u64 v[148:149], v[148:149], 0, s[2:3]
	v_lshl_add_u64 v[140:141], v[140:141], 0, s[2:3]
	s_and_b64 vcc, exec, s[20:21]
	s_waitcnt lgkmcnt(0)
	s_barrier
	s_cbranch_vccnz .LBB0_892
	.p2align 6

; __device__ void phaseB(const Params& p, char* smem) {
;     ...
;     auto cload = [&](int u, float4 (&v)[4]) {
;       const int tile = u & 127, mat = (u >> 7) & 1, e = u >> 8;
;       const float* W = (mat ? p.w_up : p.w_gate) + (size_t)e * DM * DEXP + (size_t)((tile & 15) * 64) * DEXP + (tile >> 4) * 64;
; #pragma unroll
;       for (int i = 0; i < 4; i++) v[i] = *(const float4*)&W[(size_t)(tr + 16 * i) * DEXP + tc4];
;     };
;     auto cproc = [&](int u, float4 (&v)[4]) {
;       const int tile = u & 127, mat = (u >> 7) & 1, e = u >> 8;
;       u16* WT = (mat ? p.WuT : p.WgT) + (size_t)e * DEXP * DM;
;       const int k0 = (tile & 15) * 64, n0 = (tile >> 4) * 64;
;       __syncthreads();
; #pragma unroll
;       for (int i = 0; i < 4; i++) {
;         const int k = tr + 16 * i;
;         T[(tc4 + 0) * 72 + k] = f2bf(v[i].x); T[(tc4 + 1) * 72 + k] = f2bf(v[i].y);
;         T[(tc4 + 2) * 72 + k] = f2bf(v[i].z); T[(tc4 + 3) * 72 + k] = f2bf(v[i].w);
;       }
;       __syncthreads();
;       const int n = threadIdx.x >> 2, seg = (threadIdx.x & 3) * 16;
;       const u32x4 a = *(const u32x4*)&T[n * 72 + seg], b = *(const u32x4*)&T[n * 72 + seg + 8];
;       *(u32x4*)&WT[(size_t)(n0 + n) * DM + k0 + seg] = a;
;       *(u32x4*)&WT[(size_t)(n0 + n) * DM + k0 + seg + 8] = b;
;     };
;     auto conv_range = [&](int u, int uend) -> int {
;       float4 va[4], vb[4];
;       if (u < uend) cload(u, va);
;       while (u < uend) {
;         if (u + nb < uend) cload(u + nb, vb);
;         cproc(u, va);
;         u += nb;
;         if (u >= uend) break;
;         if (u + nb < uend) cload(u + nb, va);
;         cproc(u, vb);
;         u += nb;
;       }
;       return u;
;     };
.LBB0_905:
	s_cmpk_gt_u32 s25, 0x1fff
	s_cbranch_scc1 .LBB0_916
	v_readlane_b32 s0, v240, 26
	s_bitcmp0_b32 s25, 7
	v_readlane_b32 s1, v240, 27
	v_readlane_b32 s2, v240, 28
	v_readlane_b32 s8, v240, 34
	v_readlane_b32 s9, v240, 35
	v_readlane_b32 s10, v240, 36
	v_readlane_b32 s11, v240, 37
	s_cselect_b32 s0, s9, s11
	s_cselect_b32 s1, s8, s10
	s_lshl_b32 s2, s25, 13
	s_and_b32 s2, s2, 0x7e00000
	s_add_u32 s1, s1, s2
	s_addc_u32 s0, s0, 0
	s_lshl_b32 s2, s25, 17
	s_lshl_b32 s11, s25, 15
	s_and_b32 s2, s2, 0x1e0000
	v_readlane_b32 s3, v240, 29
	s_add_u32 s1, s1, s2
	s_addc_u32 s3, s0, 0
	s_lshl_b32 s0, s25, 4
	s_lshl_b32 s2, s25, 2
	s_and_b32 s0, s0, 0x700
	s_add_u32 s0, s1, s0
	v_mov_b32_e32 v101, 0
	s_addc_u32 s1, s3, 0
	v_mov_b32_e32 v99, v101
	v_add_u32_e32 v32, 0x8000, v98
	v_mov_b32_e32 v33, v101
	v_add_u32_e32 v34, 0x10000, v98
	v_mov_b32_e32 v35, v101
	v_add_u32_e32 v36, 0x18000, v98
	v_mov_b32_e32 v37, v101
	v_lshl_add_u64 v[0:1], s[0:1], 0, v[98:99]
	v_lshl_add_u64 v[2:3], s[0:1], 0, v[32:33]
	v_lshl_add_u64 v[8:9], s[0:1], 0, v[34:35]
	v_lshl_add_u64 v[10:11], s[0:1], 0, v[36:37]
	v_lshl_add_u64 v[0:1], v[0:1], 0, v[100:101]
	v_lshl_add_u64 v[4:5], v[2:3], 0, v[100:101]
	v_lshl_add_u64 v[8:9], v[8:9], 0, v[100:101]
	v_lshl_add_u64 v[12:13], v[10:11], 0, v[100:101]
	global_load_dwordx4 v[0:3], v[0:1], off
	s_nop 0
	global_load_dwordx4 v[4:7], v[4:5], off
	s_nop 0
	global_load_dwordx4 v[8:11], v[8:9], off
	s_nop 0
	global_load_dwordx4 v[12:15], v[12:13], off
	v_mul_u32_u24_e32 v16, 0x90, v96
	v_readlane_b32 s4, v240, 30
	v_readlane_b32 s5, v240, 31
	v_readlane_b32 s6, v240, 32
	v_readlane_b32 s7, v240, 33
	v_add3_u32 v38, 0, v16, v137
	v_mul_u32_u24_e32 v16, 0x90, v135
	v_lshlrev_b32_e32 v17, 1, v97
	v_add3_u32 v39, 0, v16, v17
	s_lshl_b32 s3, s25, 6
	s_lshl_b32 s4, s24, 7
	s_lshl_b32 s5, s24, 3
	s_lshl_b32 s6, s24, 1
	s_lshl_b32 s7, s24, 16
	s_lshl_b32 s8, s24, 2
	s_lshl_b32 s9, s24, 6
	s_lshl_b32 s10, s24, 15
	v_readlane_b32 s12, v240, 38
	v_readlane_b32 s13, v240, 39
	v_readlane_b32 s14, v240, 40
	v_readlane_b32 s15, v240, 41
	s_branch .LBB0_909
.LBB0_907:
	v_cvt_pk_bf16_f32 v40, v20, s0
	s_barrier
	ds_write_b16 v38, v40
	v_cvt_pk_bf16_f32 v40, v21, s0
	ds_write_b16 v38, v40 offset:144
	v_cvt_pk_bf16_f32 v40, v22, s0
	ds_write_b16 v38, v40 offset:288
	v_cvt_pk_bf16_f32 v40, v23, s0
	ds_write_b16 v38, v40 offset:432
	v_cvt_pk_bf16_f32 v40, v16, s0
	ds_write_b16 v38, v40 offset:32
	v_cvt_pk_bf16_f32 v40, v17, s0
	ds_write_b16 v38, v40 offset:176
	v_cvt_pk_bf16_f32 v40, v18, s0
	ds_write_b16 v38, v40 offset:320
	v_cvt_pk_bf16_f32 v40, v19, s0
	ds_write_b16 v38, v40 offset:464
	v_cvt_pk_bf16_f32 v40, v28, s0
	ds_write_b16 v38, v40 offset:64
	v_cvt_pk_bf16_f32 v40, v29, s0
	ds_write_b16 v38, v40 offset:208
	v_cvt_pk_bf16_f32 v40, v30, s0
	ds_write_b16 v38, v40 offset:352
	v_cvt_pk_bf16_f32 v40, v31, s0
	ds_write_b16 v38, v40 offset:496
	v_cvt_pk_bf16_f32 v40, v24, s0
	s_add_i32 s25, s12, s24
	ds_write_b16 v38, v40 offset:96
	v_cvt_pk_bf16_f32 v40, v25, s0
	s_bitcmp0_b32 s12, 7
	ds_write_b16 v38, v40 offset:240
	v_cvt_pk_bf16_f32 v40, v26, s0
	s_cselect_b32 s11, s75, s77
	s_cselect_b32 s15, s74, s76
	ds_write_b16 v38, v40 offset:384
	v_cvt_pk_bf16_f32 v40, v27, s0
	s_add_i32 s0, s8, s2
	s_and_b32 s2, s0, 0x1c0
	s_add_i32 s0, s9, s3
	s_and_b32 s16, s0, 0x3c0
	s_ashr_i32 s0, s12, 8
	ds_write_b16 v38, v40 offset:528
	s_ashr_i32 s1, s0, 31
	s_waitcnt lgkmcnt(0)
	s_barrier
	ds_read_b128 v[40:43], v39
	ds_read_b128 v[44:47], v39 offset:16
	s_lshl_b64 s[0:1], s[0:1], 20
	s_add_u32 s0, s15, s0
	v_add_lshl_u32 v48, s2, v135, 10
	s_addc_u32 s1, s11, s1
	v_or3_b32 v48, v48, s16, v97
	s_add_i32 s3, s3, s4
	v_lshlrev_b32_e32 v48, 1, v48
	s_cmpk_gt_i32 s25, 0x1fff
	s_waitcnt lgkmcnt(1)
	global_store_dwordx4 v48, v[40:43], s[0:1]
	s_waitcnt lgkmcnt(0)
	global_store_dwordx4 v48, v[44:47], s[0:1] offset:16
	s_cselect_b64 s[0:1], -1, 0
	s_mov_b32 s2, s14
	s_mov_b32 s11, s13

; __device__ void phaseB(const Params& p, char* smem) {
;     ...
;     auto cload = [&](int u, float4 (&v)[4]) {
;       const int tile = u & 127, mat = (u >> 7) & 1, e = u >> 8;
;       const float* W = (mat ? p.w_up : p.w_gate) + (size_t)e * DM * DEXP + (size_t)((tile & 15) * 64) * DEXP + (tile >> 4) * 64;
; #pragma unroll
;       for (int i = 0; i < 4; i++) v[i] = *(const float4*)&W[(size_t)(tr + 16 * i) * DEXP + tc4];
;     };
;     auto cproc = [&](int u, float4 (&v)[4]) {
;       const int tile = u & 127, mat = (u >> 7) & 1, e = u >> 8;
;       u16* WT = (mat ? p.WuT : p.WgT) + (size_t)e * DEXP * DM;
;       const int k0 = (tile & 15) * 64, n0 = (tile >> 4) * 64;
;       __syncthreads();
; #pragma unroll
;       for (int i = 0; i < 4; i++) {
;         const int k = tr + 16 * i;
;         T[(tc4 + 0) * 72 + k] = f2bf(v[i].x); T[(tc4 + 1) * 72 + k] = f2bf(v[i].y);
;         T[(tc4 + 2) * 72 + k] = f2bf(v[i].z); T[(tc4 + 3) * 72 + k] = f2bf(v[i].w);
;       }
;       __syncthreads();
;       const int n = threadIdx.x >> 2, seg = (threadIdx.x & 3) * 16;
;       const u32x4 a = *(const u32x4*)&T[n * 72 + seg], b = *(const u32x4*)&T[n * 72 + seg + 8];
;       *(u32x4*)&WT[(size_t)(n0 + n) * DM + k0 + seg] = a;
;       *(u32x4*)&WT[(size_t)(n0 + n) * DM + k0 + seg + 8] = b;
;     };
;     auto conv_range = [&](int u, int uend) -> int {
;       float4 va[4], vb[4];
;       if (u < uend) cload(u, va);
;       while (u < uend) {
;         if (u + nb < uend) cload(u + nb, vb);
;         cproc(u, va);
;         u += nb;
;         if (u >= uend) break;
;         if (u + nb < uend) cload(u + nb, va);
;         cproc(u, vb);
;         u += nb;
;       }
;       return u;
;     };
.LBB0_909:
	s_add_i32 s12, s25, s24
	s_cmpk_lt_i32 s12, 0x2000
	s_cselect_b64 s[0:1], -1, 0
	s_cmpk_gt_i32 s12, 0x1fff
	s_cbranch_scc1 .LBB0_911
	s_ashr_i32 s14, s12, 8
	v_readlane_b32 s36, v240, 26
	s_bitcmp0_b32 s12, 7
	v_readlane_b32 s44, v240, 34
	v_readlane_b32 s45, v240, 35
	v_readlane_b32 s46, v240, 36
	v_readlane_b32 s47, v240, 37
	s_cselect_b32 s13, s45, s47
	s_cselect_b32 s16, s44, s46
	s_ashr_i32 s15, s14, 31
	s_lshl_b64 s[14:15], s[14:15], 21
	s_add_u32 s14, s16, s14
	s_addc_u32 s13, s13, s15
	s_add_i32 s15, s10, s11
	s_and_b32 s15, s15, 0x78000
	s_lshl_b32 s15, s15, 2
	s_add_u32 s14, s14, s15
	s_addc_u32 s13, s13, 0
	s_add_i32 s15, s8, s2
	s_and_b32 s15, s15, 0x1c0
	s_lshl_b32 s15, s15, 2
	s_add_u32 s14, s14, s15
	s_addc_u32 s15, s13, 0
	v_lshl_add_u64 v[16:17], s[14:15], 0, v[98:99]
	v_lshlrev_b32_e32 v100, 2, v96
	v_lshl_add_u64 v[18:19], s[14:15], 0, v[32:33]
	v_lshl_add_u64 v[24:25], s[14:15], 0, v[34:35]
	v_lshl_add_u64 v[26:27], s[14:15], 0, v[36:37]
	v_lshl_add_u64 v[16:17], v[16:17], 0, v[100:101]
	v_lshl_add_u64 v[18:19], v[18:19], 0, v[100:101]
	v_lshl_add_u64 v[24:25], v[24:25], 0, v[100:101]
	v_lshl_add_u64 v[26:27], v[26:27], 0, v[100:101]
	global_load_dwordx4 v[20:23], v[16:17], off
	s_nop 0
	global_load_dwordx4 v[16:19], v[18:19], off
	s_nop 0
	global_load_dwordx4 v[28:31], v[24:25], off
	s_nop 0
	global_load_dwordx4 v[24:27], v[26:27], off
	v_readlane_b32 s37, v240, 27
	v_readlane_b32 s38, v240, 28
	v_readlane_b32 s39, v240, 29
	v_readlane_b32 s40, v240, 30
	v_readlane_b32 s41, v240, 31
	v_readlane_b32 s42, v240, 32
	v_readlane_b32 s43, v240, 33
	v_readlane_b32 s48, v240, 38
	v_readlane_b32 s49, v240, 39
	v_readlane_b32 s50, v240, 40
	v_readlane_b32 s51, v240, 41
.LBB0_911:
	s_waitcnt vmcnt(3)
	v_cvt_pk_bf16_f32 v40, v0, s0
	s_barrier
	ds_write_b16 v38, v40
	v_cvt_pk_bf16_f32 v40, v1, s0
	ds_write_b16 v38, v40 offset:144
	v_cvt_pk_bf16_f32 v40, v2, s0
	ds_write_b16 v38, v40 offset:288
	v_cvt_pk_bf16_f32 v40, v3, s0
	ds_write_b16 v38, v40 offset:432
	s_waitcnt vmcnt(2)
	v_cvt_pk_bf16_f32 v40, v4, s0
	ds_write_b16 v38, v40 offset:32
	v_cvt_pk_bf16_f32 v40, v5, s0
	ds_write_b16 v38, v40 offset:176
	v_cvt_pk_bf16_f32 v40, v6, s0
	ds_write_b16 v38, v40 offset:320
	v_cvt_pk_bf16_f32 v40, v7, s0
	ds_write_b16 v38, v40 offset:464
	s_waitcnt vmcnt(1)
	v_cvt_pk_bf16_f32 v40, v8, s0
	ds_write_b16 v38, v40 offset:64
	v_cvt_pk_bf16_f32 v40, v9, s0
	ds_write_b16 v38, v40 offset:208
	v_cvt_pk_bf16_f32 v40, v10, s0
	ds_write_b16 v38, v40 offset:352
	v_cvt_pk_bf16_f32 v40, v11, s0
	ds_write_b16 v38, v40 offset:496
	s_waitcnt vmcnt(0)
	v_cvt_pk_bf16_f32 v40, v12, s0
	ds_write_b16 v38, v40 offset:96
	v_cvt_pk_bf16_f32 v40, v13, s0
	ds_write_b16 v38, v40 offset:240
	v_cvt_pk_bf16_f32 v40, v14, s0
	s_bitcmp0_b32 s25, 7
	ds_write_b16 v38, v40 offset:384
	v_cvt_pk_bf16_f32 v40, v15, s0
	s_cselect_b32 s13, s75, s77
	s_cselect_b32 s16, s74, s76
	ds_write_b16 v38, v40 offset:528
	s_ashr_i32 s14, s25, 8
	s_waitcnt lgkmcnt(0)
	s_barrier
	ds_read_b128 v[40:43], v39
	ds_read_b128 v[44:47], v39 offset:16
	s_and_b32 s17, s2, 0x1c0
	s_ashr_i32 s15, s14, 31
	s_and_b32 s18, s3, 0x3c0
	s_lshl_b64 s[14:15], s[14:15], 20
	v_add_lshl_u32 v48, s17, v135, 10
	s_add_u32 s14, s16, s14
	v_or3_b32 v48, v48, s18, v97
	s_addc_u32 s15, s13, s15
	v_lshlrev_b32_e32 v48, 1, v48
	s_andn2_b64 vcc, exec, s[0:1]
	s_mov_b64 s[0:1], -1
	s_waitcnt lgkmcnt(1)
	global_store_dwordx4 v48, v[40:43], s[14:15]
	s_waitcnt lgkmcnt(0)
	global_store_dwordx4 v48, v[44:47], s[14:15] offset:16
	s_cbranch_vccnz .LBB0_908
	s_add_i32 s15, s6, s25
	s_cmpk_lt_i32 s15, 0x2000
	s_cbranch_scc1 .LBB0_914
	s_add_i32 s14, s2, s5
	s_add_i32 s13, s11, s7
	s_mov_b64 s[0:1], 0

; template <bool ABF, bool BBF, class RowF, class ColF, class Epi>
; __device__ __forceinline__ void gemm_tile(char* smem, int K, RowF rowptr, ColF colptr, int ldb, Epi epi) {
;     ...
;   for (int k0 = 0; k0 < K; k0 += BK) {
;     if (k0 + BK < K) gload(k0 + BK);
;     const u16* As = As0 + cur * (GEMM_SMEM / 2);
;     const u16* Bs = As + BM * LDT;
;     {
;       bf16x8 af[2][4], bfr[2][4];
; #pragma unroll
;       for (int ks = 0; ks < 2; ks++) {
; #pragma unroll
;         for (int mi = 0; mi < 4; mi++) af[ks][mi] = *(const bf16x8*)&As[(wm * 64 + mi * 16 + l15) * LDT + (((ks * 4 + kg) ^ swz) << 3)];
; #pragma unroll
;         for (int ni = 0; ni < 4; ni++) bfr[ks][ni] = *(const bf16x8*)&Bs[(wn * 64 + ni * 16 + l15) * LDT + (((ks * 4 + kg) ^ swz) << 3)];
;       }
;       __builtin_amdgcn_sched_barrier(0);
; #pragma unroll
;       for (int ks = 0; ks < 2; ks++)
; #pragma unroll
;         for (int mi = 0; mi < 4; mi++)
; #pragma unroll
;           for (int ni = 0; ni < 4; ni++)
;             acc[mi][ni] = __builtin_amdgcn_mfma_f32_16x16x32_bf16(bfr[ks][ni], af[ks][mi], acc[mi][ni], 0, 0, 0);
;       __builtin_amdgcn_sched_barrier(0);
;     }
;     if (k0 + BK < K) sstore(cur ^ 1);
;     __syncthreads();
;     cur ^= 1;
;   }
.LBB0_1040:
	s_add_i32 s8, s8, 64
	s_xor_b32 s44, s44, 1
	v_lshl_add_u64 v[122:123], v[122:123], 0, s[2:3]
	v_lshl_add_u64 v[140:141], v[140:141], 0, s[2:3]
	v_lshl_add_u64 v[142:143], v[142:143], 0, s[2:3]
	v_lshl_add_u64 v[144:145], v[144:145], 0, s[2:3]
	v_lshl_add_u64 v[120:121], v[120:121], 0, s[2:3]
	s_and_b64 vcc, exec, s[24:25]
	s_waitcnt lgkmcnt(0)
	s_barrier
	s_cbranch_vccnz .LBB0_1045
	.p2align 6

; __device__ void phaseB(const Params& p, char* smem) {
;     ...
;     auto cload = [&](int u, float4 (&v)[4]) {
;       const int tile = u & 127, mat = (u >> 7) & 1, e = u >> 8;
;       const float* W = (mat ? p.w_up : p.w_gate) + (size_t)e * DM * DEXP + (size_t)((tile & 15) * 64) * DEXP + (tile >> 4) * 64;
; #pragma unroll
;       for (int i = 0; i < 4; i++) v[i] = *(const float4*)&W[(size_t)(tr + 16 * i) * DEXP + tc4];
;     };
;     auto cproc = [&](int u, float4 (&v)[4]) {
;       const int tile = u & 127, mat = (u >> 7) & 1, e = u >> 8;
;       u16* WT = (mat ? p.WuT : p.WgT) + (size_t)e * DEXP * DM;
;       const int k0 = (tile & 15) * 64, n0 = (tile >> 4) * 64;
;       __syncthreads();
; #pragma unroll
;       for (int i = 0; i < 4; i++) {
;         const int k = tr + 16 * i;
;         T[(tc4 + 0) * 72 + k] = f2bf(v[i].x); T[(tc4 + 1) * 72 + k] = f2bf(v[i].y);
;         T[(tc4 + 2) * 72 + k] = f2bf(v[i].z); T[(tc4 + 3) * 72 + k] = f2bf(v[i].w);
;       }
;       __syncthreads();
;       const int n = threadIdx.x >> 2, seg = (threadIdx.x & 3) * 16;
;       const u32x4 a = *(const u32x4*)&T[n * 72 + seg], b = *(const u32x4*)&T[n * 72 + seg + 8];
;       *(u32x4*)&WT[(size_t)(n0 + n) * DM + k0 + seg] = a;
;       *(u32x4*)&WT[(size_t)(n0 + n) * DM + k0 + seg + 8] = b;
;     };
.LBB0_1109:
	s_mov_b64 exec, -1
	v_readlane_b32 s8, v240, 34
	v_readlane_b32 s9, v240, 35
	v_readlane_b32 s10, v240, 36
	v_readlane_b32 s11, v240, 37
	v_and_b32_e32 v0, 63, v128
	v_and_b32_e32 v1, 15, v0
	v_lshrrev_b32_e32 v2, 4, v0
	v_lshlrev_b32_e32 v3, 13, v1
	v_lshl_add_u32 v3, v2, 4, v3
	v_add_u32_e32 v4, 0x1000, v3
	v_lshlrev_b32_e32 v5, 13, v2
	v_lshl_add_u32 v5, v1, 3, v5
	v_add_u32_e32 v74, 0x0, v5
	v_add_u32_e32 v75, 0x1000, v5
	v_add_u32_e32 v76, 0x8000, v5
	v_add_u32_e32 v77, 0x9000, v5
	v_add_u32_e32 v78, 0x10000, v5
	v_add_u32_e32 v79, 0x11000, v5
	v_add_u32_e32 v80, 0x18000, v5
	v_add_u32_e32 v81, 0x19000, v5
	v_lshrrev_b32_e32 v9, 6, v128
	s_nop 0
	v_readfirstlane_b32 s12, v9
	s_nop 3
	v_readlane_b32 s16, v240, 42
	s_nop 3
	s_lshl_b32 s16, s16, 2
	s_add_u32 s16, s16, s12
	s_add_u32 s16, s16, 12288
	s_mov_b32 s13, s16
	s_branch .Lcvtc_first

; __device__ void phaseB(const Params& p, char* smem) {
;     ...
;     auto cload = [&](int u, float4 (&v)[4]) {
;       const int tile = u & 127, mat = (u >> 7) & 1, e = u >> 8;
;       const float* W = (mat ? p.w_up : p.w_gate) + (size_t)e * DM * DEXP + (size_t)((tile & 15) * 64) * DEXP + (tile >> 4) * 64;
; #pragma unroll
;       for (int i = 0; i < 4; i++) v[i] = *(const float4*)&W[(size_t)(tr + 16 * i) * DEXP + tc4];
;     };
;     auto cproc = [&](int u, float4 (&v)[4]) {
;       const int tile = u & 127, mat = (u >> 7) & 1, e = u >> 8;
;       u16* WT = (mat ? p.WuT : p.WgT) + (size_t)e * DEXP * DM;
;       const int k0 = (tile & 15) * 64, n0 = (tile >> 4) * 64;
;       __syncthreads();
; #pragma unroll
;       for (int i = 0; i < 4; i++) {
;         const int k = tr + 16 * i;
;         T[(tc4 + 0) * 72 + k] = f2bf(v[i].x); T[(tc4 + 1) * 72 + k] = f2bf(v[i].y);
;         T[(tc4 + 2) * 72 + k] = f2bf(v[i].z); T[(tc4 + 3) * 72 + k] = f2bf(v[i].w);
;       }
;       __syncthreads();
;       const int n = threadIdx.x >> 2, seg = (threadIdx.x & 3) * 16;
;       const u32x4 a = *(const u32x4*)&T[n * 72 + seg], b = *(const u32x4*)&T[n * 72 + seg + 8];
;       *(u32x4*)&WT[(size_t)(n0 + n) * DM + k0 + seg] = a;
;       *(u32x4*)&WT[(size_t)(n0 + n) * DM + k0 + seg + 8] = b;
;     };
.Lcvtc_first:
	s_cmp_ge_u32 s16, 16384
	s_cbranch_scc1 .Lcvtc_done
	s_and_b32 s17, s16, 127
	s_lshr_b32 s18, s16, 8
	s_bitcmp1_b32 s16, 7
	s_cselect_b32 s20, s10, s8
	s_cselect_b32 s21, s11, s9
	s_cselect_b32 s22, s76, s74
	s_cselect_b32 s23, s77, s75
	s_and_b32 s19, s17, 15
	s_lshr_b32 s17, s17, 4
	s_lshl_b32 s26, s18, 21
	s_add_u32 s20, s20, s26
	s_addc_u32 s21, s21, 0
	s_lshl_b32 s26, s19, 17
	s_lshl_b32 s27, s17, 8
	s_add_u32 s26, s26, s27
	s_add_u32 s20, s20, s26
	s_addc_u32 s21, s21, 0
	s_lshl_b32 s26, s18, 20
	s_add_u32 s22, s22, s26
	s_addc_u32 s23, s23, 0
	s_lshl_b32 s26, s17, 17
	s_lshl_b32 s27, s19, 7
	s_add_u32 s26, s26, s27
	s_add_u32 s22, s22, s26
	s_addc_u32 s23, s23, 0
	global_load_dwordx4 v[10:13], v3, s[20:21] offset:0
	global_load_dwordx4 v[14:17], v3, s[20:21] offset:2048
	global_load_dwordx4 v[18:21], v4, s[20:21] offset:0
	global_load_dwordx4 v[22:25], v4, s[20:21] offset:2048
	global_load_dwordx4 v[26:29], v3, s[20:21] offset:64
	global_load_dwordx4 v[30:33], v3, s[20:21] offset:2112
	global_load_dwordx4 v[34:37], v4, s[20:21] offset:64
	global_load_dwordx4 v[38:41], v4, s[20:21] offset:2112
	global_load_dwordx4 v[42:45], v3, s[20:21] offset:128
	global_load_dwordx4 v[46:49], v3, s[20:21] offset:2176
	global_load_dwordx4 v[50:53], v4, s[20:21] offset:128
	global_load_dwordx4 v[54:57], v4, s[20:21] offset:2176
	global_load_dwordx4 v[58:61], v3, s[20:21] offset:192
	global_load_dwordx4 v[62:65], v3, s[20:21] offset:2240
	global_load_dwordx4 v[66:69], v4, s[20:21] offset:192
	global_load_dwordx4 v[70:73], v4, s[20:21] offset:2240
	s_waitcnt vmcnt(12)
	v_cvt_pk_bf16_f32 v82, v10, v14
	v_cvt_pk_bf16_f32 v83, v18, v22
	v_cvt_pk_bf16_f32 v84, v11, v15
	v_cvt_pk_bf16_f32 v85, v19, v23
	v_cvt_pk_bf16_f32 v86, v12, v16
	v_cvt_pk_bf16_f32 v87, v20, v24
	v_cvt_pk_bf16_f32 v88, v13, v17
	v_cvt_pk_bf16_f32 v89, v21, v25
	global_store_dwordx2 v74, v[82:83], s[22:23]
	global_store_dwordx2 v74, v[84:85], s[22:23] offset:2048
	global_store_dwordx2 v75, v[86:87], s[22:23]
	global_store_dwordx2 v75, v[88:89], s[22:23] offset:2048
	s_waitcnt vmcnt(12)
	v_cvt_pk_bf16_f32 v82, v26, v30
	v_cvt_pk_bf16_f32 v83, v34, v38
	v_cvt_pk_bf16_f32 v84, v27, v31
	v_cvt_pk_bf16_f32 v85, v35, v39
	v_cvt_pk_bf16_f32 v86, v28, v32
	v_cvt_pk_bf16_f32 v87, v36, v40
	v_cvt_pk_bf16_f32 v88, v29, v33
	v_cvt_pk_bf16_f32 v89, v37, v41
	global_store_dwordx2 v76, v[82:83], s[22:23]
	global_store_dwordx2 v76, v[84:85], s[22:23] offset:2048
	global_store_dwordx2 v77, v[86:87], s[22:23]
	global_store_dwordx2 v77, v[88:89], s[22:23] offset:2048
	s_waitcnt vmcnt(12)
	v_cvt_pk_bf16_f32 v82, v42, v46
	v_cvt_pk_bf16_f32 v83, v50, v54
	v_cvt_pk_bf16_f32 v84, v43, v47
	v_cvt_pk_bf16_f32 v85, v51, v55
	v_cvt_pk_bf16_f32 v86, v44, v48
	v_cvt_pk_bf16_f32 v87, v52, v56
	v_cvt_pk_bf16_f32 v88, v45, v49
	v_cvt_pk_bf16_f32 v89, v53, v57
	global_store_dwordx2 v78, v[82:83], s[22:23]
	global_store_dwordx2 v78, v[84:85], s[22:23] offset:2048
	global_store_dwordx2 v79, v[86:87], s[22:23]
	global_store_dwordx2 v79, v[88:89], s[22:23] offset:2048
	s_waitcnt vmcnt(12)
	v_cvt_pk_bf16_f32 v82, v58, v62
	v_cvt_pk_bf16_f32 v83, v66, v70
	v_cvt_pk_bf16_f32 v84, v59, v63
	v_cvt_pk_bf16_f32 v85, v67, v71
	v_cvt_pk_bf16_f32 v86, v60, v64
	v_cvt_pk_bf16_f32 v87, v68, v72
	v_cvt_pk_bf16_f32 v88, v61, v65
	v_cvt_pk_bf16_f32 v89, v69, v73
	global_store_dwordx2 v80, v[82:83], s[22:23]
	global_store_dwordx2 v80, v[84:85], s[22:23] offset:2048
	global_store_dwordx2 v81, v[86:87], s[22:23]
	global_store_dwordx2 v81, v[88:89], s[22:23] offset:2048
	s_branch .Lcvtc_next

; __device__ void phaseD(const Params& p, char* smem) {
;     ...
;     auto rload = [&](int it, RB& r) {
;       r.a = *(const float4*)&xrow[16 * it];
;       r.g = *(const float4*)&p.ln1_g[256 * w + 16 * it + 4 * kg];
;       r.b = *(const float4*)&p.ln1_b[256 * w + 16 * it + 4 * kg];
;       const int kb = 256 * w + 16 * it + 4 * kg;
; #pragma unroll
;       for (int i = 0; i < 4; i++) {
;         const float* we = p.w_er + (size_t)(kb + i) * 64 + l15;
; #pragma unroll
;         for (int nt = 0; nt < 4; nt++) r.we[i][nt] = we[16 * nt];
;         r.wg[i] = (l15 < 8) ? p.w_gr[(size_t)(kb + i) * 8 + l15] : 0.f;
;       }
;     };
;     auto rcomp = [&](const RB& r) {
;       const float av[4] = {(r.a.x - rmu) * rrs * r.g.x + r.b.x, (r.a.y - rmu) * rrs * r.g.y + r.b.y,
;                            (r.a.z - rmu) * rrs * r.g.z + r.b.z, (r.a.w - rmu) * rrs * r.g.w + r.b.w};
; #pragma unroll
;       for (int i = 0; i < 4; i++) {
; #pragma unroll
;         for (int nt = 0; nt < 4; nt++) acc[nt] = __builtin_amdgcn_mfma_f32_16x16x4f32(av[i], r.we[i][nt], acc[nt], 0, 0, 0);
;         acc[4] = __builtin_amdgcn_mfma_f32_16x16x4f32(av[i], r.wg[i], acc[4], 0, 0, 0);
;       }
;     };
;     {
;       RB r0, r1;
;       rload(0, r0);
;       for (int it = 0; it < 16; it += 2) {
;         rload(it + 1, r1);
;         rcomp(r0);
;         if (it + 2 < 16) rload(it + 2, r0);
;         rcomp(r1);
;       }
.LBB0_1184:
	s_waitcnt vmcnt(18)
	v_sub_f32_e32 v16, v16, v46
	v_mul_f32_e32 v16, v47, v16
	s_waitcnt vmcnt(16)
	v_fma_f32 v12, v16, v20, v12
	s_add_i32 s16, s16, 2
	s_add_u32 s0, s0, 0x80
	v_lshl_add_u64 v[104:105], v[104:105], 0, s[2:3]
	v_lshl_add_u64 v[102:103], v[102:103], 0, s[4:5]
	s_waitcnt vmcnt(15)
	v_mfma_f32_16x16x4_f32 v[24:27], v12, v155, v[24:27]
	s_addc_u32 s1, s1, 0
	v_lshl_add_u64 v[100:101], v[100:101], 0, s[2:3]
	v_lshl_add_u64 v[98:99], v[98:99], 0, s[4:5]
	v_lshl_add_u64 v[96:97], v[96:97], 0, s[4:5]
	v_lshl_add_u64 v[94:95], v[94:95], 0, s[2:3]
	s_andn2_b64 vcc, exec, s[12:13]
	s_waitcnt vmcnt(14)
	v_mfma_f32_16x16x4_f32 v[28:31], v12, v156, v[28:31]
	s_waitcnt vmcnt(13)
	v_mfma_f32_16x16x4_f32 v[32:35], v12, v157, v[32:35]
	s_waitcnt vmcnt(12)
	v_mfma_f32_16x16x4_f32 v[36:39], v12, v158, v[36:39]
	v_mfma_f32_16x16x4_f32 v[40:43], v12, v159, v[40:43]
	v_sub_f32_e32 v12, v17, v46
	v_mul_f32_e32 v12, v47, v12
	v_fma_f32 v12, v12, v21, v13
	s_waitcnt vmcnt(11)
	s_nop 0
	v_mfma_f32_16x16x4_f32 v[24:27], v12, v173, v[24:27]
	s_waitcnt vmcnt(10)
	v_mfma_f32_16x16x4_f32 v[28:31], v12, v174, v[28:31]
	s_waitcnt vmcnt(9)
	v_mfma_f32_16x16x4_f32 v[32:35], v12, v175, v[32:35]
	s_waitcnt vmcnt(8)
	v_mfma_f32_16x16x4_f32 v[36:39], v12, v176, v[36:39]
	v_mfma_f32_16x16x4_f32 v[40:43], v12, v177, v[40:43]
	v_sub_f32_e32 v12, v18, v46
	v_mul_f32_e32 v12, v47, v12
	v_fma_f32 v12, v12, v22, v14
	s_waitcnt vmcnt(7)
	s_nop 0
	v_mfma_f32_16x16x4_f32 v[24:27], v12, v178, v[24:27]
	s_waitcnt vmcnt(6)
	v_mfma_f32_16x16x4_f32 v[28:31], v12, v179, v[28:31]
	s_waitcnt vmcnt(5)
	v_mfma_f32_16x16x4_f32 v[106:109], v12, v180, v[32:35]
	s_waitcnt vmcnt(4)
	v_mfma_f32_16x16x4_f32 v[110:113], v12, v181, v[36:39]
	v_mfma_f32_16x16x4_f32 v[156:159], v12, v172, v[40:43]
	v_sub_f32_e32 v12, v19, v46
	v_mul_f32_e32 v12, v47, v12
	v_fmac_f32_e32 v15, v12, v23
	s_waitcnt vmcnt(3)
	s_nop 0
	v_mfma_f32_16x16x4_f32 v[32:35], v15, v182, v[24:27]
	s_waitcnt vmcnt(2)
	v_mfma_f32_16x16x4_f32 v[36:39], v15, v183, v[28:31]
	s_waitcnt vmcnt(1)
	v_mfma_f32_16x16x4_f32 v[28:31], v15, v184, v[106:109]
	s_waitcnt vmcnt(0)
	v_mfma_f32_16x16x4_f32 v[40:43], v15, v115, v[110:113]
	v_mfma_f32_16x16x4_f32 v[24:27], v15, v114, v[156:159]
	s_cbranch_vccz .LBB0_1202
	.p2align 6

; template <bool ABF, bool BBF, class RowF, class ColF, class Epi>
; __device__ __forceinline__ void gemm_tile(char* smem, int K, RowF rowptr, ColF colptr, int ldb, Epi epi) {
;     ...
;   for (int k0 = 0; k0 < K; k0 += BK) {
;     if (k0 + BK < K) gload(k0 + BK);
;     const u16* As = As0 + cur * (GEMM_SMEM / 2);
;     const u16* Bs = As + BM * LDT;
;     {
;       bf16x8 af[2][4], bfr[2][4];
; #pragma unroll
;       for (int ks = 0; ks < 2; ks++) {
; #pragma unroll
;         for (int mi = 0; mi < 4; mi++) af[ks][mi] = *(const bf16x8*)&As[(wm * 64 + mi * 16 + l15) * LDT + (((ks * 4 + kg) ^ swz) << 3)];
; #pragma unroll
;         for (int ni = 0; ni < 4; ni++) bfr[ks][ni] = *(const bf16x8*)&Bs[(wn * 64 + ni * 16 + l15) * LDT + (((ks * 4 + kg) ^ swz) << 3)];
;       }
;       __builtin_amdgcn_sched_barrier(0);
; #pragma unroll
;       for (int ks = 0; ks < 2; ks++)
; #pragma unroll
;         for (int mi = 0; mi < 4; mi++)
; #pragma unroll
;           for (int ni = 0; ni < 4; ni++)
;             acc[mi][ni] = __builtin_amdgcn_mfma_f32_16x16x32_bf16(bfr[ks][ni], af[ks][mi], acc[mi][ni], 0, 0, 0);
;       __builtin_amdgcn_sched_barrier(0);
;     }
;     if (k0 + BK < K) sstore(cur ^ 1);
;     __syncthreads();
;     cur ^= 1;
;   }
.LBB0_1277:
	s_add_i32 s2, s2, 64
	s_xor_b32 s27, s27, 1
	v_lshl_add_u64 v[140:141], v[140:141], 0, s[4:5]
	v_lshl_add_u64 v[142:143], v[142:143], 0, s[4:5]
	v_lshl_add_u64 v[144:145], v[144:145], 0, s[4:5]
	v_lshl_add_u64 v[146:147], v[146:147], 0, s[4:5]
	v_lshl_add_u64 v[132:133], v[132:133], 0, s[4:5]
	v_lshl_add_u64 v[134:135], v[134:135], 0, s[4:5]
	v_lshl_add_u64 v[136:137], v[136:137], 0, s[4:5]
	v_lshl_add_u64 v[138:139], v[138:139], 0, s[4:5]
	s_and_b64 vcc, exec, s[18:19]
	s_waitcnt lgkmcnt(0)
	s_barrier
	s_cbranch_vccnz .LBB0_1282
	.p2align 6

; template <bool ABF, bool BBF, class RowF, class ColF, class Epi>
; __device__ __forceinline__ void gemm_tile(char* smem, int K, RowF rowptr, ColF colptr, int ldb, Epi epi) {
;     ...
;   for (int k0 = 0; k0 < K; k0 += BK) {
;     if (k0 + BK < K) gload(k0 + BK);
;     const u16* As = As0 + cur * (GEMM_SMEM / 2);
;     const u16* Bs = As + BM * LDT;
;     {
;       bf16x8 af[2][4], bfr[2][4];
; #pragma unroll
;       for (int ks = 0; ks < 2; ks++) {
; #pragma unroll
;         for (int mi = 0; mi < 4; mi++) af[ks][mi] = *(const bf16x8*)&As[(wm * 64 + mi * 16 + l15) * LDT + (((ks * 4 + kg) ^ swz) << 3)];
; #pragma unroll
;         for (int ni = 0; ni < 4; ni++) bfr[ks][ni] = *(const bf16x8*)&Bs[(wn * 64 + ni * 16 + l15) * LDT + (((ks * 4 + kg) ^ swz) << 3)];
;       }
;       __builtin_amdgcn_sched_barrier(0);
; #pragma unroll
;       for (int ks = 0; ks < 2; ks++)
; #pragma unroll
;         for (int mi = 0; mi < 4; mi++)
; #pragma unroll
;           for (int ni = 0; ni < 4; ni++)
;             acc[mi][ni] = __builtin_amdgcn_mfma_f32_16x16x32_bf16(bfr[ks][ni], af[ks][mi], acc[mi][ni], 0, 0, 0);
;       __builtin_amdgcn_sched_barrier(0);
;     }
;     if (k0 + BK < K) sstore(cur ^ 1);
;     __syncthreads();
;     cur ^= 1;
;   }
.LBB0_1359:
	s_add_i32 s2, s2, 64
	s_xor_b32 s47, s47, 1
	v_lshl_add_u64 v[96:97], v[96:97], 0, s[4:5]
	v_lshl_add_u64 v[100:101], v[100:101], 0, s[6:7]
	v_lshl_add_u64 v[102:103], v[102:103], 0, s[6:7]
	v_lshl_add_u64 v[104:105], v[104:105], 0, s[6:7]
	v_lshl_add_u64 v[106:107], v[106:107], 0, s[6:7]
	s_and_b64 vcc, exec, s[18:19]
	s_waitcnt lgkmcnt(0)
	s_barrier
	s_cbranch_vccnz .LBB0_1364
	.p2align 6

; __device__ void phaseF(const Params& p, char* smem) {
;   int* s_off = (int*)(smem + 2 * GEMM_SMEM);
;   int* s_rb = s_off + 72;
;   moe_prefix(p, s_off, s_rb);
;   const int tid = threadIdx.x, lane = tid & 63, w = tid >> 6;
;   for (int rp = blockIdx.x * 4 + w; rp < NTOK / 2; rp += gridDim.x * 4) {
;     int sl[2][2];
; #pragma unroll
;     for (int h = 0; h < 2; h++) {
;       const int row = rp * 2 + h;
;       const int2 te = *(const int2*)&p.tok_e[row * 2], tp = *(const int2*)&p.tok_pos[row * 2];
.LBB0_1428:
	s_or_b64 exec, exec, s[0:1]
	v_readlane_b32 s2, v240, 42
	s_movk_i32 s0, 0x2000
	s_waitcnt lgkmcnt(0)
	v_lshl_add_u32 v23, s2, 2, v129
	v_cmp_gt_i32_e32 vcc, s0, v23
	s_barrier
	v_readlane_b32 s3, v240, 43
	s_and_saveexec_b64 s[0:1], vcc
	s_cbranch_execz .LBB0_1431
	v_and_b32_e32 v2, 0xfc, v127
	v_readlane_b32 s4, v240, 26
	v_readlane_b32 s0, v240, 1
	v_lshlrev_b32_e32 v0, 2, v2
	v_mov_b32_e32 v1, 0
	v_readlane_b32 s18, v240, 40
	v_readlane_b32 s19, v240, 41
	v_readlane_b32 s1, v240, 2
	v_readlane_b32 s5, v240, 27
	v_readlane_b32 s6, v240, 28
	v_readlane_b32 s7, v240, 29
	v_readlane_b32 s8, v240, 30
	v_readlane_b32 s9, v240, 31
	v_lshl_add_u64 v[8:9], s[18:19], 0, v[0:1]
	v_lshl_add_u64 v[10:11], s[84:85], 0, v[0:1]
	v_lshlrev_b32_e32 v2, 1, v2
	v_mov_b32_e32 v3, v1
	v_lshl_add_u64 v[16:17], s[86:87], 0, v[0:1]
	v_lshlrev_b32_e32 v0, 1, v129
	s_lshl_b32 s3, s0, 2
	v_lshl_add_u64 v[12:13], s[56:57], 0, v[2:3]
	v_lshl_add_u64 v[14:15], s[60:61], 0, v[2:3]
	v_lshl_add_u32 v18, s2, 3, v0
	s_lshl_b32 s5, s0, 3
	v_lshl_add_u32 v20, s2, 4, v148
	s_lshl_b32 s6, s0, 4
	s_mov_b64 s[0:1], 0
	s_add_i32 s7, 0, 0x10000
	s_mov_b32 s2, 0x3f9837f0
	s_mov_b32 s4, 0x3a800000
	v_mov_b32_e32 v22, 0x3727c5ac
	s_mov_b32 s8, 0x800000
	s_movk_i32 s9, 0x1fff
	v_readlane_b32 s10, v240, 32
	v_readlane_b32 s11, v240, 33
	v_readlane_b32 s12, v240, 34
	v_readlane_b32 s13, v240, 35
	v_readlane_b32 s14, v240, 36
	v_readlane_b32 s15, v240, 37
	v_readlane_b32 s16, v240, 38
	v_readlane_b32 s17, v240, 39
	.p2align 6
